# sample-sequence conv groups placed on decode-first workgroups only (vcu%16 in {8,9})
# baseline (speedup 1.0000x reference)
.LBB0_498:
	v_mbcnt_lo_u32_b32 v0, -1, 0
	v_mbcnt_hi_u32_b32 v0, -1, v0
	s_mov_b64 s[14:15], s[96:97]
	v_add_u32_e32 v6, s73, v0
	s_load_dwordx4 s[16:19], s[14:15], 0xd8
	s_load_dwordx2 s[40:41], s[14:15], 0x20
	s_load_dwordx8 s[4:11], s[14:15], 0x78
	s_and_b32 s98, s92, 14
	s_xor_b32 s98, s98, 8
	s_or_b32 s98, s98, s93
	s_cmp_eq_u32 s98, 0
	s_cbranch_scc0 .Lsconv_pf_done
	s_waitcnt lgkmcnt(0)
	s_lshr_b32 s98, s92, 4
	s_lshl_b32 s98, s98, 1
	s_and_b32 s99, s92, 1
	s_or_b32 s98, s98, s99
	s_mul_i32 s98, s98, 0xf000
	s_add_u32 s98, s40, s98
	s_addc_u32 s99, s41, 0
	v_lshlrev_b32_e32 v249, 7, v0
	global_load_dword v252, v249, s[98:99]
	s_add_u32 s98, s98, 0x2000
	s_addc_u32 s99, s99, 0
	global_load_dword v252, v249, s[98:99]
	s_add_u32 s98, s98, 0x2000
	s_addc_u32 s99, s99, 0
	global_load_dword v252, v249, s[98:99]
	s_add_u32 s98, s98, 0x2000
	s_addc_u32 s99, s99, 0
	global_load_dword v252, v249, s[98:99]
	s_add_u32 s98, s98, 0x2000
	s_addc_u32 s99, s99, 0
	global_load_dword v252, v249, s[98:99]
	s_add_u32 s98, s98, 0x2000
	s_addc_u32 s99, s99, 0
	global_load_dword v252, v249, s[98:99]
	s_add_u32 s98, s98, 0x2000
	s_addc_u32 s99, s99, 0
	global_load_dword v252, v249, s[98:99]

.LBB0_513:
	s_and_b32 s4, s12, 0x77
	s_cmp_lg_u32 s4, 0x40
	s_cselect_b64 s[4:5], -1, 0
	s_bfe_u32 s14, s12, 0x10003
	s_lshr_b32 s12, s12, 7
	s_lshl_b32 s12, s12, 1
	s_or_b32 s12, s12, s14
	s_cmp_gt_i32 s12, 31
	s_cselect_b64 s[14:15], -1, 0
	s_or_b64 s[4:5], s[4:5], s[14:15]
	s_andn2_b64 vcc, exec, s[4:5]
	s_cbranch_vccz .LBB0_548
	v_mov_b32_e32 v111, 0
	s_add_i32 s4, s34, 63
	v_mov_b32_e32 v113, v111
	s_ashr_i32 s14, s4, 6
	v_lshl_add_u64 v[0:1], s[16:17], 0, v[112:113]
	s_mov_b64 s[4:5], 0x8178000
	v_lshl_add_u64 v[92:93], v[0:1], 0, s[4:5]
	s_mul_i32 s5, s12, 0xf000
	v_lshl_add_u64 v[88:89], s[6:7], 0, v[112:113]
	s_mul_hi_i32 s4, s12, 0xf000
	s_add_u32 s6, s16, s5
	s_addc_u32 s7, s17, s4
	s_add_u32 s6, s6, 0x8178800
	s_addc_u32 s7, s7, 0
	v_lshl_add_u64 v[94:95], s[8:9], 0, v[112:113]
	s_add_u32 s8, s40, s5
	v_add_u32_e32 v0, 0, v112
	v_lshl_add_u64 v[90:91], s[42:43], 0, v[110:111]
	v_lshl_add_u64 v[96:97], s[10:11], 0, v[112:113]
	v_lshl_add_u64 v[98:99], s[18:19], 0, v[110:111]
	s_mul_hi_i32 s15, s14, 0xf000
	s_mul_i32 s24, s14, 0xf000
	s_addc_u32 s9, s41, s4
	v_add_u32_e32 v134, 0x2000, v0
	s_mov_b32 s25, 0xffff0000
	s_mov_b64 s[10:11], 0x1000
	s_mov_b64 s[16:17], 0x1800
	s_mov_b64 s[40:41], 0x2000
	s_mov_b64 s[42:43], 0x2800
	v_mov_b32_e32 v135, 0x358637bd
	s_mov_b32 s26, 0xf800000
	v_mov_b32_e32 v136, 0x260
	s_movk_i32 s27, 0x7fff
	v_lshlrev_b32_e32 v110, 1, v114
	s_brev_b32 s28, 64
	s_mov_b32 s29, 0x2001000
	s_branch .LBB0_516

.LBB0_548:
	s_and_b32 s98, s92, 14
	s_cmp_eq_u32 s98, 8
	s_cbranch_scc0 .Lscopy_done
	s_cmp_eq_u32 s93, 0
	s_cbranch_scc1 .Lscopy_done
	s_load_dwordx2 s[80:81], s[96:97], 0x20
	s_load_dwordx2 s[100:101], s[96:97], 0xd8
	s_lshr_b32 s98, s92, 4
	s_lshl_b32 s98, s98, 1
	s_and_b32 s99, s92, 1
	s_or_b32 s98, s98, s99
	s_mul_i32 s98, s98, 30
	s_lshl_b32 s99, s93, 2
	s_add_i32 s98, s98, s99
	s_lshl_b32 s98, s98, 11
	v_mbcnt_lo_u32_b32 v253, -1, 0
	v_mbcnt_hi_u32_b32 v253, -1, v253
	v_lshlrev_b32_e32 v253, 5, v253
	s_waitcnt lgkmcnt(0)
	s_add_u32 s80, s80, s98
	s_addc_u32 s81, s81, 0
	s_add_u32 s100, s100, s98
	s_addc_u32 s101, s101, 0
	s_add_u32 s100, s100, 0x8176000
	s_addc_u32 s101, s101, 0
	global_load_dwordx4 v[236:239], v253, s[80:81]
	global_load_dwordx4 v[240:243], v253, s[80:81] offset:16
	global_load_dwordx4 v[244:247], v253, s[80:81] offset:2048
	global_load_dwordx4 v[228:231], v253, s[80:81] offset:2064
	s_waitcnt vmcnt(0)
	global_store_dwordx4 v253, v[236:239], s[100:101]
	global_store_dwordx4 v253, v[240:243], s[100:101] offset:16
	global_store_dwordx4 v253, v[244:247], s[100:101] offset:2048
	global_store_dwordx4 v253, v[228:231], s[100:101] offset:2064
	s_cmp_eq_u32 s93, 7
	s_cbranch_scc1 .Lscopy_done
	s_add_u32 s80, s80, 0x1000
	s_addc_u32 s81, s81, 0
	s_add_u32 s100, s100, 0x1000
	s_addc_u32 s101, s101, 0
	s_nop 1
	global_load_dwordx4 v[236:239], v253, s[80:81]
	global_load_dwordx4 v[240:243], v253, s[80:81] offset:16
	global_load_dwordx4 v[244:247], v253, s[80:81] offset:2048
	global_load_dwordx4 v[228:231], v253, s[80:81] offset:2064
	s_waitcnt vmcnt(0)
	global_store_dwordx4 v253, v[236:239], s[100:101]
	global_store_dwordx4 v253, v[240:243], s[100:101] offset:16
	global_store_dwordx4 v253, v[244:247], s[100:101] offset:2048
	global_store_dwordx4 v253, v[228:231], s[100:101] offset:2064
